# attn0: O stores and previous-group O loads as full 128-byte lines (4 dwordx4 per lane) through a per-wave LDS staging transpose
# speedup vs baseline: 1.0082x; 1.0039x over previous
.LBB0_431:
	v_writelane_b32 v255, s76, 19
	s_and_b32 s33, s7, -2
	v_writelane_b32 v255, s75, 20
	s_lshr_b32 s77, 0x80, s33
	s_lshl_b32 s75, s71, 10
	s_sub_i32 s76, 12, s33
	s_add_i32 s77, s77, -1
	s_add_i32 s75, s75, 0
	s_add_u32 s4, s0, 0x19000000
	s_addc_u32 s5, s1, 0
	v_writelane_b32 v255, s7, 21
	s_and_b64 s[2:3], exec, s[2:3]
	s_cselect_b32 s3, s83, s5
	v_writelane_b32 v255, s82, 22
	s_cselect_b32 s2, s82, s4
	s_add_u32 s4, s0, 0xb00000
	v_writelane_b32 v255, s83, 23
	v_writelane_b32 v255, s4, 24
	s_addc_u32 s4, s1, 0
	s_cmp_gt_i32 s71, 3
	v_lshlrev_b32_e32 v2, 1, v243
	v_lshrrev_b32_e32 v4, 5, v243
	s_cselect_b64 s[92:93], -1, 0
	s_lshl_b32 s6, s71, 4
	v_writelane_b32 v255, s4, 25
	v_and_b32_e32 v8, 8, v2
	v_lshlrev_b32_e32 v2, 3, v4
	v_lshlrev_b32_e32 v4, 4, v243
	v_mov_b32_e32 v5, v0
	s_ashr_i32 s7, s6, 31
	s_add_i32 s4, s6, 0x7fffffc0
	v_lshl_add_u64 v[6:7], s[2:3], 0, v[4:5]
	s_lshl_b32 s2, s71, 5
	v_writelane_b32 v255, s6, 26
	s_and_b32 s78, s2, 0x60
	s_lshl_b32 s78, s78, 5
	s_lshl_b32 s2, -1, s76
	v_writelane_b32 v255, s7, 27
	s_not_b32 s73, s2
	v_readlane_b32 s2, v255, 17
	v_lshrrev_b32_e32 v1, 1, v242
	s_and_b32 s4, s4, 0x7fffffe0
	v_mov_b32_e32 v3, v0
	v_readlane_b32 s3, v255, 18
	v_and_b32_e32 v150, 31, v242
	v_and_b32_e32 v1, 4, v1
	v_and_b32_e32 v9, 19, v242
	v_lshl_add_u64 v[116:117], v[6:7], 0, s[78:79]
	v_lshl_add_u64 v[118:119], s[2:3], 0, v[4:5]
	v_lshl_add_u64 v[120:121], s[18:19], 0, v[2:3]
	v_lshrrev_b32_e32 v247, 3, v243
	v_and_b32_e32 v112, 7, v247
	v_and_b32_e32 v113, 7, v243
	v_xor_b32_e32 v112, v112, v113
	v_lshlrev_b32_e32 v112, 4, v112
	v_mov_b32_e32 v113, 0
	v_lshl_add_u64 v[114:115], s[18:19], 0, v[112:113]
	v_and_b32_e32 v113, 31, v243
	v_lshlrev_b32_e32 v246, 7, v113
	v_and_b32_e32 v113, 7, v113
	v_lshl_or_b32 v246, v113, 4, v246
	v_lshrrev_b32_e32 v113, 5, v243
	v_lshl_or_b32 v113, v113, 3, v246
	s_add_i32 s100, s33, 14
	s_lshl_b32 s100, 1, s100
	s_mov_b32 s101, 0
	s_cmp_gt_i32 s10, 0
	v_or_b32_e32 v3, 2, v2
	v_or_b32_e32 v4, 3, v2
	v_or_b32_e32 v5, 4, v2
	v_or_b32_e32 v6, 5, v2
	v_or_b32_e32 v7, 6, v2
	v_or_b32_e32 v10, 7, v2
	v_or_b32_e32 v11, 16, v2
	s_waitcnt lgkmcnt(3)
	v_or_b32_e32 v12, 17, v2
	s_waitcnt lgkmcnt(2)
	v_or_b32_e32 v13, 18, v2
	s_waitcnt lgkmcnt(0)
	v_or_b32_e32 v14, 19, v2
	v_or_b32_e32 v15, 20, v2
	v_or_b32_e32 v16, 21, v2
	v_or_b32_e32 v17, 22, v2
	v_or_b32_e32 v18, 23, v2
	v_or_b32_e32 v19, 1, v2
	v_or_b32_e32 v151, s4, v150
	v_writelane_b32 v255, s10, 28
	s_cselect_b64 s[88:89], -1, 0
	v_lshl_add_u32 v152, v243, 4, 0
	v_cmp_gt_u32_e64 s[2:3], 32, v243
	v_cmp_gt_u32_e64 s[4:5], v2, v150
	v_cmp_lt_u32_e64 s[6:7], v2, v150
	v_cmp_gt_u32_e64 s[8:9], v3, v150
	v_cmp_gt_u32_e64 s[10:11], v4, v150
	v_cmp_gt_u32_e64 s[12:13], v5, v150
	v_cmp_gt_u32_e64 s[14:15], v6, v150
	v_cmp_gt_u32_e64 s[16:17], v7, v150
	v_cmp_gt_u32_e64 s[18:19], v10, v150
	v_cmp_gt_u32_e64 s[20:21], v11, v150
	v_cmp_gt_u32_e64 s[22:23], v12, v150
	v_cmp_gt_u32_e64 s[24:25], v13, v150
	v_cmp_gt_u32_e64 s[26:27], v14, v150
	v_cmp_gt_u32_e64 s[28:29], v15, v150
	v_cmp_gt_u32_e64 s[30:31], v16, v150
	v_cmp_gt_u32_e64 s[34:35], v17, v150
	v_cmp_gt_u32_e64 s[36:37], v18, v150
	v_cmp_lt_u32_e64 s[38:39], v19, v150
	v_cmp_lt_u32_e64 s[40:41], v3, v150
	v_cmp_lt_u32_e64 s[42:43], v4, v150
	v_cmp_lt_u32_e64 s[44:45], v5, v150
	v_cmp_lt_u32_e64 s[46:47], v6, v150
	v_cmp_lt_u32_e64 s[48:49], v7, v150
	v_cmp_lt_u32_e64 s[50:51], v10, v150
	v_cmp_lt_u32_e64 s[52:53], v11, v150
	v_cmp_lt_u32_e64 s[54:55], v12, v150
	v_cmp_lt_u32_e64 s[56:57], v13, v150
	v_cmp_lt_u32_e64 s[58:59], v14, v150
	v_cmp_lt_u32_e64 s[60:61], v15, v150
	v_cmp_lt_u32_e64 s[62:63], v16, v150
	v_cmp_lt_u32_e64 s[64:65], v17, v150
	v_cmp_lt_u32_e64 s[66:67], v18, v150
	v_or3_b32 v153, v1, v9, v8
	s_lshl_b32 s86, s70, 6
	v_lshlrev_b32_e32 v122, 1, v2
	s_branch .LBB0_433

.LBB0_437:
	s_lshl_b32 s98, s74, 4
	s_add_i32 s98, s98, s72
	s_lshl_b32 s98, s98, 19
	s_mov_b32 s99, 0
	s_lshl_b32 s69, s86, 13
	s_and_b32 s69, s69, 0x80000
	s_or_b32 s84, s69, 0x20000
	s_lshl_b32 s69, s70, 6
	s_and_b32 s94, s69, 64
	s_lshl_b64 s[82:83], s[78:79], 1
	s_lshl_b32 s69, s72, 2
	v_readlane_b32 s72, v255, 24
	v_lshl_add_u64 v[142:143], v[118:119], 0, s[98:99]
	v_lshl_add_u64 v[144:145], v[120:121], 0, s[82:83]
	v_lshl_add_u64 v[64:65], v[114:115], 0, s[82:83]
	s_add_u32 s82, s72, s69
	v_readlane_b32 s69, v255, 25
	v_or_b32_e32 v123, s87, v150
	s_addc_u32 s83, s69, 0
	s_lshl_b32 s78, s68, 1
	s_mov_b32 s95, 0
	s_branch .LBB0_439

.LBB0_440:
	s_and_b32 vcc_lo, s85, 0x1e000
	s_add_i32 vcc_lo, s75, vcc_lo
	s_mov_b32 vcc_hi, m0
	s_mov_b32 m0, vcc_lo
	s_nop 0
	global_load_lds_dwordx4 v[2:3], off
	s_mov_b32 m0, vcc_hi
	s_add_i32 s69, s69, 1
	s_addk_i32 s85, 0x2000
	s_cmp_ge_i32 s69, s68
	v_lshl_add_u64 v[2:3], v[2:3], 0, s[78:79]
	s_cbranch_scc0 .LBB0_440
	s_add_i32 s72, s72, s71
	s_lshl_b32 s68, s72, 5
	s_lshl_b32 s98, s72, 12
	s_mov_b32 s99, 0
	v_lshl_add_u64 v[2:3], v[142:143], 0, s[98:99]
	global_load_dwordx4 v[92:95], v[2:3], off
	global_load_dwordx4 v[88:91], v[2:3], off offset:1024
	global_load_dwordx4 v[84:87], v[2:3], off offset:2048
	global_load_dwordx4 v[80:83], v[2:3], off offset:3072
	s_ashr_i32 s69, s68, s76
	s_and_b32 s68, s68, s73
	v_or_b32_e32 v1, s68, v150
	v_lshlrev_b32_e32 v1, s33, v1
	s_add_i32 s69, s69, s87
	v_add_u32_e32 v2, s69, v1
	v_ashrrev_i32_e32 v3, 31, v2
	v_lshlrev_b64 v[4:5], 11, v[2:3]
	v_lshlrev_b64 v[2:3], 6, v[2:3]
	v_lshl_add_u64 v[148:149], v[144:145], 0, v[4:5]
	v_lshl_add_u64 v[146:147], s[82:83], 0, v[2:3]
	v_or_b32_e32 v250, s68, v247
	v_lshlrev_b32_e32 v250, s33, v250
	v_add_u32_e32 v250, s69, v250
	v_ashrrev_i32_e32 v251, 31, v250
	v_lshlrev_b64 v[250:251], 11, v[250:251]
	v_lshl_add_u64 v[248:249], v[64:65], 0, v[250:251]
	s_sub_i32 s84, s72, s71
	s_lshr_b32 vcc_lo, s71, 1
	s_add_i32 s84, s84, vcc_lo
	s_add_i32 s84, s84, 8
	s_and_b32 s84, s84, 15
	s_lshl_b32 s84, s84, 13
	s_and_b32 vcc_lo, s71, 1
	s_lshl_b32 vcc_lo, vcc_lo, 12
	s_or_b32 s84, s84, vcc_lo
	v_add_u32_e32 v244, s84, v113
	v_add_u32_e32 v245, s84, v152
	s_and_b64 vcc, exec, s[88:89]
	s_cbranch_vccz .LBB0_443
	global_load_dword v154, v[146:147], off
	global_load_dwordx4 v[124:127], v[248:249], off
	v_lshl_add_u64 v[250:251], v[248:249], 0, s[100:101]
	global_load_dwordx4 v[128:131], v[250:251], off
	v_lshl_add_u64 v[250:251], v[250:251], 0, s[100:101]
	global_load_dwordx4 v[132:135], v[250:251], off
	v_lshl_add_u64 v[250:251], v[250:251], 0, s[100:101]
	global_load_dwordx4 v[136:139], v[250:251], off
	s_branch .LBB0_444

.LBB0_466:
	v_cmp_lt_i32_e32 vcc, v155, v156
	v_cndmask_b32_e64 v4, 0, 1, s[88:89]
	v_cmp_ne_u32_e64 s[68:69], 1, v4
	v_cndmask_b32_e32 v2, v68, v155, vcc
	v_lshlrev_b32_e32 v2, 2, v2
	ds_bpermute_b32 v2, v2, v6
	s_andn2_b64 vcc, exec, s[88:89]
	s_waitcnt lgkmcnt(0)
	v_add_f32_e32 v3, v6, v2
	v_rcp_f32_e32 v2, v3
	v_log_f32_e32 v3, v3
	s_nop 0
	v_add_f32_e32 v1, v1, v3
	s_cbranch_vccnz .LBB0_485
	v_max_f32_e32 v3, v1, v1
	s_waitcnt vmcnt(0)
	ds_write_b128 v245, v[124:127]
	ds_write_b128 v245, v[128:131] offset:1024
	ds_write_b128 v245, v[132:135] offset:2048
	ds_write_b128 v245, v[136:139] offset:3072
	s_waitcnt lgkmcnt(0)
	ds_read_b64 v[138:139], v244
	v_xor_b32_e32 v246, 16, v244
	ds_read_b64 v[136:137], v246
	v_xor_b32_e32 v246, 32, v244
	ds_read_b64 v[134:135], v246
	v_xor_b32_e32 v246, 48, v244
	ds_read_b64 v[132:133], v246
	v_xor_b32_e32 v246, 64, v244
	ds_read_b64 v[130:131], v246
	v_xor_b32_e32 v246, 80, v244
	ds_read_b64 v[128:129], v246
	v_xor_b32_e32 v246, 96, v244
	ds_read_b64 v[126:127], v246
	v_xor_b32_e32 v246, 112, v244
	ds_read_b64 v[124:125], v246
	s_waitcnt lgkmcnt(0)
	v_max_f32_e32 v4, v154, v154
	v_max_f32_e32 v6, v4, v3
	v_sub_f32_e32 v1, v1, v6
	v_sub_f32_e32 v3, v154, v6
	v_exp_f32_e32 v1, v1
	v_exp_f32_e32 v3, v3
	s_nop 0
	v_add_f32_e32 v4, v1, v3
	v_rcp_f32_e32 v5, v4
	v_log_f32_e32 v7, v4
	v_mul_f32_e32 v4, v1, v5
	v_pk_mul_f32 v[2:3], v[2:3], v[4:5]
	v_add_f32_e32 v1, v6, v7
	v_pk_mul_f32 v[6:7], v[32:33], v[2:3] op_sel_hi:[1,0]
	s_and_b64 vcc, exec, s[68:69]
	v_pk_mul_f32 v[8:9], v[34:35], v[2:3] op_sel_hi:[1,0]
	s_cbranch_vccnz .LBB0_469

.LBB0_469:
	v_mov_b32_e32 v4, v2
	v_mov_b32_e32 v5, v2
	v_cvt_pk_bf16_f32 v6, v6, v7
	v_cvt_pk_bf16_f32 v7, v8, v9
	ds_write_b64 v244, v[6:7]
	v_pk_mul_f32 v[6:7], v[36:37], v[4:5]
	s_and_b64 vcc, exec, s[68:69]
	v_pk_mul_f32 v[8:9], v[38:39], v[4:5]
	s_cbranch_vccnz .LBB0_471
	s_waitcnt vmcnt(7)
	v_lshlrev_b32_e32 v10, 16, v136
	v_and_b32_e32 v11, 0xffff0000, v136
	v_pk_fma_f32 v[6:7], v[2:3], v[10:11], v[6:7] op_sel:[1,0,0]
	v_lshlrev_b32_e32 v10, 16, v137
	v_and_b32_e32 v11, 0xffff0000, v137
	v_pk_fma_f32 v[8:9], v[2:3], v[10:11], v[8:9] op_sel:[1,0,0]
.LBB0_471:
	v_cvt_pk_bf16_f32 v6, v6, v7
	v_cvt_pk_bf16_f32 v7, v8, v9
	v_xor_b32_e32 v246, 16, v244
	ds_write_b64 v246, v[6:7]
	v_pk_mul_f32 v[6:7], v[40:41], v[4:5]
	s_and_b64 vcc, exec, s[68:69]
	v_pk_mul_f32 v[8:9], v[42:43], v[4:5]
	s_cbranch_vccnz .LBB0_473
	s_waitcnt vmcnt(7)
	v_lshlrev_b32_e32 v10, 16, v134
	v_and_b32_e32 v11, 0xffff0000, v134
	v_pk_fma_f32 v[6:7], v[2:3], v[10:11], v[6:7] op_sel:[1,0,0]
	v_lshlrev_b32_e32 v10, 16, v135
	v_and_b32_e32 v11, 0xffff0000, v135
	v_pk_fma_f32 v[8:9], v[2:3], v[10:11], v[8:9] op_sel:[1,0,0]
.LBB0_473:
	v_cvt_pk_bf16_f32 v6, v6, v7
	v_cvt_pk_bf16_f32 v7, v8, v9
	v_xor_b32_e32 v246, 32, v244
	ds_write_b64 v246, v[6:7]
	v_pk_mul_f32 v[6:7], v[44:45], v[4:5]
	s_and_b64 vcc, exec, s[68:69]
	v_pk_mul_f32 v[8:9], v[46:47], v[4:5]
	s_cbranch_vccnz .LBB0_475
	s_waitcnt vmcnt(7)
	v_lshlrev_b32_e32 v10, 16, v132
	v_and_b32_e32 v11, 0xffff0000, v132
	v_pk_fma_f32 v[6:7], v[2:3], v[10:11], v[6:7] op_sel:[1,0,0]
	v_lshlrev_b32_e32 v10, 16, v133
	v_and_b32_e32 v11, 0xffff0000, v133
	v_pk_fma_f32 v[8:9], v[2:3], v[10:11], v[8:9] op_sel:[1,0,0]
.LBB0_475:
	v_cvt_pk_bf16_f32 v6, v6, v7
	v_cvt_pk_bf16_f32 v7, v8, v9
	v_xor_b32_e32 v246, 48, v244
	ds_write_b64 v246, v[6:7]
	v_pk_mul_f32 v[6:7], v[16:17], v[4:5]
	s_and_b64 vcc, exec, s[68:69]
	v_pk_mul_f32 v[8:9], v[18:19], v[4:5]
	s_cbranch_vccnz .LBB0_477
	s_waitcnt vmcnt(7)
	v_lshlrev_b32_e32 v10, 16, v130
	v_and_b32_e32 v11, 0xffff0000, v130
	v_pk_fma_f32 v[6:7], v[2:3], v[10:11], v[6:7] op_sel:[1,0,0]
	v_lshlrev_b32_e32 v10, 16, v131
	v_and_b32_e32 v11, 0xffff0000, v131
	v_pk_fma_f32 v[8:9], v[2:3], v[10:11], v[8:9] op_sel:[1,0,0]
.LBB0_477:
	v_cvt_pk_bf16_f32 v6, v6, v7
	v_cvt_pk_bf16_f32 v7, v8, v9
	v_xor_b32_e32 v246, 64, v244
	ds_write_b64 v246, v[6:7]
	v_pk_mul_f32 v[6:7], v[20:21], v[4:5]
	s_and_b64 vcc, exec, s[68:69]
	v_pk_mul_f32 v[8:9], v[22:23], v[4:5]
	s_cbranch_vccnz .LBB0_479
	s_waitcnt vmcnt(7)
	v_lshlrev_b32_e32 v10, 16, v128
	v_and_b32_e32 v11, 0xffff0000, v128
	v_pk_fma_f32 v[6:7], v[2:3], v[10:11], v[6:7] op_sel:[1,0,0]
	v_lshlrev_b32_e32 v10, 16, v129
	v_and_b32_e32 v11, 0xffff0000, v129
	v_pk_fma_f32 v[8:9], v[2:3], v[10:11], v[8:9] op_sel:[1,0,0]
.LBB0_479:
	v_cvt_pk_bf16_f32 v6, v6, v7
	v_cvt_pk_bf16_f32 v7, v8, v9
	v_xor_b32_e32 v246, 80, v244
	ds_write_b64 v246, v[6:7]
	v_pk_mul_f32 v[6:7], v[24:25], v[4:5]
	s_and_b64 vcc, exec, s[68:69]
	v_pk_mul_f32 v[8:9], v[26:27], v[4:5]
	s_cbranch_vccnz .LBB0_481
	s_waitcnt vmcnt(7)
	v_lshlrev_b32_e32 v10, 16, v126
	v_and_b32_e32 v11, 0xffff0000, v126
	v_pk_fma_f32 v[6:7], v[2:3], v[10:11], v[6:7] op_sel:[1,0,0]
	v_lshlrev_b32_e32 v10, 16, v127
	v_and_b32_e32 v11, 0xffff0000, v127
	v_pk_fma_f32 v[8:9], v[2:3], v[10:11], v[8:9] op_sel:[1,0,0]
.LBB0_481:
	v_cvt_pk_bf16_f32 v6, v6, v7
	v_cvt_pk_bf16_f32 v7, v8, v9
	v_xor_b32_e32 v246, 96, v244
	ds_write_b64 v246, v[6:7]
	v_pk_mul_f32 v[6:7], v[28:29], v[4:5]
	s_and_b64 vcc, exec, s[68:69]
	v_pk_mul_f32 v[4:5], v[30:31], v[4:5]
	s_cbranch_vccnz .LBB0_483
	s_waitcnt vmcnt(7)
	v_lshlrev_b32_e32 v8, 16, v124
	v_and_b32_e32 v9, 0xffff0000, v124
	v_pk_fma_f32 v[6:7], v[2:3], v[8:9], v[6:7] op_sel:[1,0,0]
	v_lshlrev_b32_e32 v8, 16, v125
	v_and_b32_e32 v9, 0xffff0000, v125
	v_pk_fma_f32 v[4:5], v[2:3], v[8:9], v[4:5] op_sel:[1,0,0]
.LBB0_483:
	v_cvt_pk_bf16_f32 v2, v6, v7
	v_cvt_pk_bf16_f32 v3, v4, v5
	v_xor_b32_e32 v246, 112, v244
	ds_write_b64 v246, v[2:3]
	s_waitcnt lgkmcnt(0)
	ds_read_b128 v[124:127], v245
	ds_read_b128 v[128:131], v245 offset:1024
	ds_read_b128 v[132:135], v245 offset:2048
	ds_read_b128 v[136:139], v245 offset:3072
	s_waitcnt lgkmcnt(3)
	global_store_dwordx4 v[248:249], v[124:127], off
	v_lshl_add_u64 v[248:249], v[248:249], 0, s[100:101]
	s_waitcnt lgkmcnt(2)
	global_store_dwordx4 v[248:249], v[128:131], off
	v_lshl_add_u64 v[248:249], v[248:249], 0, s[100:101]
	s_waitcnt lgkmcnt(1)
	global_store_dwordx4 v[248:249], v[132:135], off
	v_lshl_add_u64 v[248:249], v[248:249], 0, s[100:101]
	s_waitcnt lgkmcnt(0)
	global_store_dwordx4 v[248:249], v[136:139], off
	s_and_saveexec_b64 s[68:69], s[2:3]
	s_cbranch_execz .LBB0_438
	global_store_dword v[146:147], v1, off
	s_branch .LBB0_438
